# retention scan: cross-product phase (state x Q) moved above the S-prime barrier so the barrier wait overlaps its MFMAs
# speedup vs baseline: 1.0110x; 1.0058x over previous
; #define LAS __attribute__((address_space(3)))
; __device__ __forceinline__ unsigned cvtpk(float lo, float hi) { unsigned r; asm volatile("v_cvt_pk_bf16_f32 %0, %1, %2" : "=v"(r) : "v"(lo), "v"(hi)); return r; }
; #define MF16(a, b, c) __builtin_amdgcn_mfma_f32_16x16x32_bf16((a), (b), (c), 0, 0, 0)
; __device__ __forceinline__ void ret_item(LAS unsigned char* lds, const bf16_t* proj, bf16_t* OD, int b, int h, int dir, int vs, float lg2) {
;     ...
;         RBAR();
;         {   f32x4 sa0 = (f32x4){0.f, 0.f, 0.f, 0.f}, sa1 = sa0;
;             s16x4 fq[2][2]; bf16x8 fk0[2], fk1[2];
;     ...
;             LDS_S(0, 0);
; #pragma unroll
;             for (int s = 0; s < 8; ++s) { if (s < 7) LDS_S((s + 1) & 1, s + 1); SCHED();
;                 const bf16x8 bq = cat(fq[s & 1][0], fq[s & 1][1]);
;                 __builtin_amdgcn_s_setprio(1); sa0 = MF16(fk0[s & 1], bq, sa0); sa1 = MF16(fk1[s & 1], bq, sa1); __builtin_amdgcn_s_setprio(0); SCHED(); }
;     ...
; #pragma unroll
;             for (int tt = 0; tt < 2; ++tt) { const f32x4 sv = tt ? sa1 : sa0; const int dt = dir ? (sjt0 + tt - sit) : (sit - sjt0 - tt);
;                 const float cs = dt <= 0 ? 1.f : dt == 1 ? c16 : dt == 2 ? c32 : c48; float w[4];
; #pragma unroll
;                 for (int r = 0; r < 4; ++r) { const bool on = dt > 0 || (dt == 0 && (dir ? (4 * g + r > l15) : (l15 >= 4 * g + r))); w[r] = on ? sv[r] * d4[r] * cs : 0.f; }
;                 u32x2 pkd; pkd.x = cvtpk(w[0], w[1]); pkd.y = cvtpk(w[2], w[3]);
;                 *(LAS u32x2*)(lds + SP + (16 * sit + l15) * RSS + (16 * (sjt0 + tt) + 4 * g) * 2) = pkd; }
;         }
;         RBAR();
;         f32x4 acc[4];
; #pragma unroll
;         for (int it = 0; it < 4; ++it) acc[it] = (f32x4){0.f, 0.f, 0.f, 0.f};
;         {   bf16x8 ca[2][4];
;     ...
;             LDS_C(0, 0);
; #pragma unroll
;             for (int s = 0; s < 8; ++s) { if (s < 7) LDS_C((s + 1) & 1, s + 1); SCHED();
;                 u32x4 bw; bw.x = cvtpk(st[2 * s][0], st[2 * s][1]); bw.y = cvtpk(st[2 * s][2], st[2 * s][3]); bw.z = cvtpk(st[2 * s + 1][0], st[2 * s + 1][1]); bw.w = cvtpk(st[2 * s + 1][2], st[2 * s + 1][3]);
;                 const bf16x8 bs = __builtin_bit_cast(bf16x8, bw);
;                 __builtin_amdgcn_s_setprio(1);
; #pragma unroll
;                 for (int it = 0; it < 4; ++it) acc[it] = MF16(bs, ca[s & 1][it], acc[it]);
;                 __builtin_amdgcn_s_setprio(0); SCHED(); }
.LBB0_140:
	s_add_i32 s20, s16, -1
	v_mov_b32_e32 v105, s20
	s_waitcnt lgkmcnt(0)
	s_barrier
	v_cndmask_b32_e64 v176, v104, v105, s[36:37]
	ds_read2_b64 v[104:107], v229 offset1:2
	ds_read_b128 v[108:111], v230 offset:36864
	ds_read_b128 v[112:115], v230 offset:46080
	ds_read2_b64 v[116:119], v229 offset0:8 offset1:10
	ds_read_b128 v[120:123], v230 offset:36928
	ds_read_b128 v[124:127], v230 offset:46144
	s_setprio 1
	s_waitcnt lgkmcnt(4)
	v_mfma_f32_16x16x32_bf16 v[108:111], v[108:111], v[104:107], 0
	s_waitcnt lgkmcnt(3)
	v_mfma_f32_16x16x32_bf16 v[104:107], v[112:115], v[104:107], 0
	s_setprio 0
	ds_read2_b64 v[112:115], v229 offset0:16 offset1:18
	ds_read_b128 v[128:131], v230 offset:36992
	ds_read_b128 v[132:135], v230 offset:46208
	s_setprio 1
	s_waitcnt lgkmcnt(4)
	v_mfma_f32_16x16x32_bf16 v[108:111], v[120:123], v[116:119], v[108:111]
	s_waitcnt lgkmcnt(3)
	v_mfma_f32_16x16x32_bf16 v[104:107], v[124:127], v[116:119], v[104:107]
	s_setprio 0
	ds_read2_b64 v[116:119], v229 offset0:24 offset1:26
	ds_read_b128 v[120:123], v230 offset:37056
	ds_read_b128 v[124:127], v230 offset:46272
	s_setprio 1
	s_waitcnt lgkmcnt(4)
	v_mfma_f32_16x16x32_bf16 v[108:111], v[128:131], v[112:115], v[108:111]
	s_waitcnt lgkmcnt(3)
	v_mfma_f32_16x16x32_bf16 v[104:107], v[132:135], v[112:115], v[104:107]
	s_setprio 0
	ds_read2_b64 v[112:115], v229 offset0:32 offset1:34
	ds_read_b128 v[128:131], v230 offset:37120
	ds_read_b128 v[132:135], v230 offset:46336
	s_setprio 1
	s_waitcnt lgkmcnt(4)
	v_mfma_f32_16x16x32_bf16 v[108:111], v[120:123], v[116:119], v[108:111]
	s_waitcnt lgkmcnt(3)
	v_mfma_f32_16x16x32_bf16 v[104:107], v[124:127], v[116:119], v[104:107]
	s_setprio 0
	ds_read2_b64 v[116:119], v229 offset0:40 offset1:42
	ds_read_b128 v[120:123], v230 offset:37184
	ds_read_b128 v[124:127], v230 offset:46400
	s_setprio 1
	s_waitcnt lgkmcnt(4)
	v_mfma_f32_16x16x32_bf16 v[108:111], v[128:131], v[112:115], v[108:111]
	s_waitcnt lgkmcnt(3)
	v_mfma_f32_16x16x32_bf16 v[104:107], v[132:135], v[112:115], v[104:107]
	s_setprio 0
	ds_read2_b64 v[112:115], v229 offset0:48 offset1:50
	ds_read_b128 v[128:131], v230 offset:37248
	ds_read_b128 v[132:135], v230 offset:46464
	s_setprio 1
	s_waitcnt lgkmcnt(4)
	v_mfma_f32_16x16x32_bf16 v[108:111], v[120:123], v[116:119], v[108:111]
	s_waitcnt lgkmcnt(3)
	v_mfma_f32_16x16x32_bf16 v[104:107], v[124:127], v[116:119], v[104:107]
	s_setprio 0
	ds_read2_b64 v[116:119], v229 offset0:56 offset1:58
	ds_read_b128 v[120:123], v230 offset:37312
	ds_read_b128 v[124:127], v230 offset:46528
	s_setprio 1
	s_waitcnt lgkmcnt(4)
	v_mfma_f32_16x16x32_bf16 v[108:111], v[128:131], v[112:115], v[108:111]
	s_waitcnt lgkmcnt(3)
	v_mfma_f32_16x16x32_bf16 v[104:107], v[132:135], v[112:115], v[104:107]
	s_setprio 0
	s_setprio 1
	s_waitcnt lgkmcnt(1)
	v_mfma_f32_16x16x32_bf16 v[108:111], v[120:123], v[116:119], v[108:111]
	s_waitcnt lgkmcnt(0)
	v_mfma_f32_16x16x32_bf16 v[104:107], v[124:127], v[116:119], v[104:107]
	s_setprio 0
	s_nop 4
	v_mul_f32_e32 v108, v199, v108
	v_mul_f32_e32 v109, v200, v109
	v_mul_f32_e32 v110, v201, v110
	v_mul_f32_e32 v108, v206, v108
	v_mul_f32_e32 v109, v206, v109
	v_mul_f32_e32 v110, v206, v110
	v_mul_f32_e32 v111, v202, v111
	v_mul_f32_e32 v104, v199, v104
	v_mul_f32_e32 v105, v200, v105
	v_mul_f32_e32 v106, v201, v106
	v_cndmask_b32_e64 v108, 0, v108, s[38:39]
	v_cndmask_b32_e64 v109, 0, v109, s[40:41]
	v_cndmask_b32_e64 v110, 0, v110, s[42:43]
	v_mul_f32_e32 v111, v206, v111
	v_mul_f32_e32 v104, v207, v104
	v_mul_f32_e32 v105, v207, v105
	v_mul_f32_e32 v106, v207, v106
	v_mul_f32_e32 v107, v202, v107
	v_cndmask_b32_e64 v111, 0, v111, s[44:45]
	v_cvt_pk_bf16_f32 v108, v108, v109
	v_cvt_pk_bf16_f32 v109, v110, v111
	v_add_u32_e32 v110, s17, v205
	v_cndmask_b32_e64 v104, 0, v104, s[46:47]
	v_cndmask_b32_e64 v105, 0, v105, s[48:49]
	v_cndmask_b32_e64 v106, 0, v106, s[50:51]
	v_mul_f32_e32 v107, v207, v107
	ds_write_b64 v110, v[108:109]
	v_cndmask_b32_e64 v107, 0, v107, s[52:53]
	v_cvt_pk_bf16_f32 v104, v104, v105
	v_cvt_pk_bf16_f32 v105, v106, v107
	v_add_u32_e32 v106, s18, v205
	ds_write_b64 v106, v[104:105]
	ds_read_b128 v[104:107], v231
	ds_read_b128 v[108:111], v231 offset:64
	ds_read_b128 v[112:115], v231 offset:9216
	ds_read_b128 v[116:119], v231 offset:9280
	ds_read_b128 v[120:123], v231 offset:18432
	ds_read_b128 v[124:127], v231 offset:18496
	ds_read_b128 v[128:131], v231 offset:27648
	ds_read_b128 v[132:135], v231 offset:27712
	v_cvt_pk_bf16_f32 v136, v40, v41
	v_cvt_pk_bf16_f32 v137, v42, v43
	v_cvt_pk_bf16_f32 v138, v52, v53
	v_cvt_pk_bf16_f32 v139, v54, v55
	s_setprio 1
	s_waitcnt lgkmcnt(7)
	v_mfma_f32_16x16x32_bf16 v[104:107], v[136:139], v[104:107], 0
	s_waitcnt lgkmcnt(5)
	v_mfma_f32_16x16x32_bf16 v[112:115], v[136:139], v[112:115], 0
	s_waitcnt lgkmcnt(3)
	v_mfma_f32_16x16x32_bf16 v[120:123], v[136:139], v[120:123], 0
	s_waitcnt lgkmcnt(1)
	v_mfma_f32_16x16x32_bf16 v[128:131], v[136:139], v[128:131], 0
	s_setprio 0
	ds_read_b128 v[136:139], v231 offset:128
	ds_read_b128 v[140:143], v231 offset:9344
	ds_read_b128 v[144:147], v231 offset:18560
	ds_read_b128 v[148:151], v231 offset:27776
	v_cvt_pk_bf16_f32 v152, v48, v49
	v_cvt_pk_bf16_f32 v153, v50, v51
	v_cvt_pk_bf16_f32 v154, v44, v45
	v_cvt_pk_bf16_f32 v155, v46, v47
	s_setprio 1
	v_mfma_f32_16x16x32_bf16 v[104:107], v[152:155], v[108:111], v[104:107]
	v_mfma_f32_16x16x32_bf16 v[108:111], v[152:155], v[116:119], v[112:115]
	v_mfma_f32_16x16x32_bf16 v[112:115], v[152:155], v[124:127], v[120:123]
	s_waitcnt lgkmcnt(4)
; __device__ __forceinline__ unsigned cvtpk(float lo, float hi) { unsigned r; asm volatile("v_cvt_pk_bf16_f32 %0, %1, %2" : "=v"(r) : "v"(lo), "v"(hi)); return r; }
; #define MF16(a, b, c) __builtin_amdgcn_mfma_f32_16x16x32_bf16((a), (b), (c), 0, 0, 0)
; __device__ __forceinline__ unsigned cvtpk(float lo, float hi) { unsigned r; asm volatile("v_cvt_pk_bf16_f32 %0, %1, %2" : "=v"(r) : "v"(lo), "v"(hi)); return r; }
; #define SCHED() __builtin_amdgcn_sched_barrier(0)
; #define LDS_C(buf, s) do { _Pragma("unroll") for (int it = 0; it < 4; ++it) ca[buf][it] = *(const LAS bf16x8*)(pCq + 16 * it * RSQ + 64 * (s)); } while (0)
; __device__ __forceinline__ void ret_item(LAS unsigned char* lds, const bf16_t* proj, bf16_t* OD, int b, int h, int dir, int vs, float lg2) {
;     ...
;         {   bf16x8 ca[2][4];
;     ...
;             LDS_C(0, 0);
; #pragma unroll
;             for (int s = 0; s < 8; ++s) { if (s < 7) LDS_C((s + 1) & 1, s + 1); SCHED();
;                 u32x4 bw; bw.x = cvtpk(st[2 * s][0], st[2 * s][1]); bw.y = cvtpk(st[2 * s][2], st[2 * s][3]); bw.z = cvtpk(st[2 * s + 1][0], st[2 * s + 1][1]); bw.w = cvtpk(st[2 * s + 1][2], st[2 * s + 1][3]);
;                 const bf16x8 bs = __builtin_bit_cast(bf16x8, bw);
;                 __builtin_amdgcn_s_setprio(1);
; #pragma unroll
;                 for (int it = 0; it < 4; ++it) acc[it] = MF16(bs, ca[s & 1][it], acc[it]);
;                 __builtin_amdgcn_s_setprio(0); SCHED(); }
	v_mfma_f32_16x16x32_bf16 v[116:119], v[152:155], v[132:135], v[128:131]
	s_setprio 0
	ds_read_b128 v[120:123], v231 offset:192
	ds_read_b128 v[124:127], v231 offset:9408
	ds_read_b128 v[128:131], v231 offset:18624
	ds_read_b128 v[132:135], v231 offset:27840
	v_cvt_pk_bf16_f32 v152, v68, v69
	v_cvt_pk_bf16_f32 v153, v70, v71
	v_cvt_pk_bf16_f32 v154, v64, v65
	v_cvt_pk_bf16_f32 v155, v66, v67
	s_setprio 1
	s_waitcnt lgkmcnt(7)
	v_mfma_f32_16x16x32_bf16 v[104:107], v[152:155], v[136:139], v[104:107]
	s_waitcnt lgkmcnt(6)
	v_mfma_f32_16x16x32_bf16 v[108:111], v[152:155], v[140:143], v[108:111]
	s_waitcnt lgkmcnt(5)
	v_mfma_f32_16x16x32_bf16 v[112:115], v[152:155], v[144:147], v[112:115]
	s_waitcnt lgkmcnt(4)
	v_mfma_f32_16x16x32_bf16 v[116:119], v[152:155], v[148:151], v[116:119]
	s_setprio 0
	ds_read_b128 v[136:139], v231 offset:256
	ds_read_b128 v[140:143], v231 offset:9472
	ds_read_b128 v[144:147], v231 offset:18688
	ds_read_b128 v[148:151], v231 offset:27904
	v_cvt_pk_bf16_f32 v152, v60, v61
	v_cvt_pk_bf16_f32 v153, v62, v63
	v_cvt_pk_bf16_f32 v154, v56, v57
	v_cvt_pk_bf16_f32 v155, v58, v59
	s_setprio 1
	s_waitcnt lgkmcnt(7)
	v_mfma_f32_16x16x32_bf16 v[104:107], v[152:155], v[120:123], v[104:107]
	s_waitcnt lgkmcnt(6)
	v_mfma_f32_16x16x32_bf16 v[108:111], v[152:155], v[124:127], v[108:111]
	s_waitcnt lgkmcnt(5)
	v_mfma_f32_16x16x32_bf16 v[112:115], v[152:155], v[128:131], v[112:115]
	s_waitcnt lgkmcnt(4)
	v_mfma_f32_16x16x32_bf16 v[116:119], v[152:155], v[132:135], v[116:119]
	s_setprio 0
	ds_read_b128 v[120:123], v231 offset:320
	ds_read_b128 v[124:127], v231 offset:9536
	ds_read_b128 v[128:131], v231 offset:18752
	ds_read_b128 v[132:135], v231 offset:27968
	v_cvt_pk_bf16_f32 v152, v88, v89
	v_cvt_pk_bf16_f32 v153, v90, v91
	v_cvt_pk_bf16_f32 v154, v80, v81
	v_cvt_pk_bf16_f32 v155, v82, v83
	s_setprio 1
	s_waitcnt lgkmcnt(7)
	v_mfma_f32_16x16x32_bf16 v[104:107], v[152:155], v[136:139], v[104:107]
	s_waitcnt lgkmcnt(6)
	v_mfma_f32_16x16x32_bf16 v[108:111], v[152:155], v[140:143], v[108:111]
	s_waitcnt lgkmcnt(5)
	v_mfma_f32_16x16x32_bf16 v[112:115], v[152:155], v[144:147], v[112:115]
	s_waitcnt lgkmcnt(4)
	v_mfma_f32_16x16x32_bf16 v[116:119], v[152:155], v[148:151], v[116:119]
	s_setprio 0
	ds_read_b128 v[136:139], v231 offset:384
	ds_read_b128 v[140:143], v231 offset:9600
	ds_read_b128 v[144:147], v231 offset:18816
	ds_read_b128 v[148:151], v231 offset:28032
	v_cvt_pk_bf16_f32 v152, v76, v77
	v_cvt_pk_bf16_f32 v153, v78, v79
	v_cvt_pk_bf16_f32 v154, v72, v73
	v_cvt_pk_bf16_f32 v155, v74, v75
	s_setprio 1
	s_waitcnt lgkmcnt(7)
	v_mfma_f32_16x16x32_bf16 v[104:107], v[152:155], v[120:123], v[104:107]
	s_waitcnt lgkmcnt(6)
	v_mfma_f32_16x16x32_bf16 v[108:111], v[152:155], v[124:127], v[108:111]
	s_waitcnt lgkmcnt(5)
	v_mfma_f32_16x16x32_bf16 v[112:115], v[152:155], v[128:131], v[112:115]
	s_waitcnt lgkmcnt(4)
	v_mfma_f32_16x16x32_bf16 v[116:119], v[152:155], v[132:135], v[116:119]
	s_setprio 0
	ds_read_b128 v[120:123], v231 offset:448
	ds_read_b128 v[124:127], v231 offset:9664
	ds_read_b128 v[128:131], v231 offset:18880
	ds_read_b128 v[132:135], v231 offset:28096
	v_cvt_pk_bf16_f32 v152, v92, v93
	v_cvt_pk_bf16_f32 v153, v94, v95
	v_cvt_pk_bf16_f32 v154, v84, v85
	v_cvt_pk_bf16_f32 v155, v86, v87
	s_setprio 1
	s_waitcnt lgkmcnt(7)
	v_mfma_f32_16x16x32_bf16 v[104:107], v[152:155], v[136:139], v[104:107]
	s_waitcnt lgkmcnt(6)
	v_mfma_f32_16x16x32_bf16 v[108:111], v[152:155], v[140:143], v[108:111]
	s_waitcnt lgkmcnt(5)
	v_mfma_f32_16x16x32_bf16 v[112:115], v[152:155], v[144:147], v[112:115]
	s_waitcnt lgkmcnt(4)
	v_mfma_f32_16x16x32_bf16 v[116:119], v[152:155], v[148:151], v[116:119]
	s_setprio 0
	v_cvt_pk_bf16_f32 v136, v96, v97
	v_cvt_pk_bf16_f32 v137, v98, v99
	v_cvt_pk_bf16_f32 v138, v100, v101
	v_cvt_pk_bf16_f32 v139, v102, v103
	s_setprio 1
	s_waitcnt lgkmcnt(3)
	v_mfma_f32_16x16x32_bf16 v[104:107], v[136:139], v[120:123], v[104:107]
	s_waitcnt lgkmcnt(2)
	v_mfma_f32_16x16x32_bf16 v[108:111], v[136:139], v[124:127], v[108:111]
	s_waitcnt lgkmcnt(1)
	v_mfma_f32_16x16x32_bf16 v[112:115], v[136:139], v[128:131], v[112:115]
	s_waitcnt lgkmcnt(0)
	v_mfma_f32_16x16x32_bf16 v[116:119], v[136:139], v[132:135], v[116:119]
	s_setprio 0
	s_waitcnt lgkmcnt(0)
	s_barrier
; #define LAS __attribute__((address_space(3)))
; __device__ __forceinline__ unsigned cvtpk(float lo, float hi) { unsigned r; asm volatile("v_cvt_pk_bf16_f32 %0, %1, %2" : "=v"(r) : "v"(lo), "v"(hi)); return r; }
; __device__ __forceinline__ s16x4 trd(LAS unsigned char* p) { return __builtin_bit_cast(s16x4, __builtin_amdgcn_ds_read_tr16_b64_v4i16((LAS s16x4*)p)); }
; __device__ __forceinline__ bf16x8 cat(s16x4 a, s16x4 b) { return (bf16x8){a[0], a[1], a[2], a[3], b[0], b[1], b[2], b[3]}; }
; #define MF16(a, b, c) __builtin_amdgcn_mfma_f32_16x16x32_bf16((a), (b), (c), 0, 0, 0)
; __device__ __forceinline__ unsigned cvtpk(float lo, float hi) { unsigned r; asm volatile("v_cvt_pk_bf16_f32 %0, %1, %2" : "=v"(r) : "v"(lo), "v"(hi)); return r; }
; #define SCHED() __builtin_amdgcn_sched_barrier(0)
; __device__ __forceinline__ void ret_item(LAS unsigned char* lds, const bf16_t* proj, bf16_t* OD, int b, int h, int dir, int vs, float lg2) {
;     ...
;         bf16x8 bv[2], ia[2][4];
; #pragma unroll
;         for (int s = 0; s < 2; ++s) { bv[s] = cat(trd(pVt + 32 * s * RSV), trd(pVt + (32 * s + 4) * RSV));
; #pragma unroll
;             for (int it = 0; it < 4; ++it) ia[s][it] = *(const LAS bf16x8*)(pIs + 16 * it * RSS + 64 * s); }
;         s16x4 ua[2][4][2];
;     ...
;         LDS_U(0, 0);
;         SCHED();
; #pragma unroll
;         for (int it = 0; it < 4; ++it) { const int ex = dir ? 3 - it : it; const float cq = qdl * (ex == 0 ? 1.f : ex == 1 ? c16 : ex == 2 ? c32 : c48); acc[it] = acc[it] * cq; }
; #pragma unroll
;         for (int s = 0; s < 2; ++s)
; #pragma unroll
;             for (int it = 0; it < 4; ++it) acc[it] = MF16(bv[s], ia[s][it], acc[it]);
;         SCHED();
; #pragma unroll
;         for (int i = 0; i < 16; ++i) st[i] = st[i] * cd;
;         bf16x8 bvd[2];
; #pragma unroll
;         for (int s = 0; s < 2; ++s) { const float ck = (dir ? s : 1 - s) ? c32 : 1.f; float e[8];
; #pragma unroll
;             for (int jj = 0; jj < 8; ++jj) e[jj] = bf2f((unsigned short)bv[s][jj]) * (kd8[jj] * ck);
;             u32x4 bw; bw.x = cvtpk(e[0], e[1]); bw.y = cvtpk(e[2], e[3]); bw.z = cvtpk(e[4], e[5]); bw.w = cvtpk(e[6], e[7]);
;             bvd[s] = __builtin_bit_cast(bf16x8, bw); }
	ds_read_b64_tr_b16 v[140:141], v232
	ds_read_b64_tr_b16 v[142:143], v232 offset:1088
	ds_read_b64_tr_b16 v[136:137], v232 offset:8704
	ds_read_b64_tr_b16 v[138:139], v232 offset:9792
	ds_read_b128 v[144:147], v233
	ds_read_b128 v[148:151], v233 offset:64
	ds_read_b128 v[152:155], v233 offset:2304
	ds_read_b128 v[156:159], v233 offset:2368
	ds_read_b128 v[236:239], v233 offset:4608
	ds_read_b128 v[240:243], v233 offset:4672
	ds_read_b128 v[244:247], v233 offset:6912
	ds_read_b128 v[248:251], v233 offset:6976
	v_add_u32_e32 v235, v204, v203
	ds_read_b64_tr_b16 v[128:129], v235 offset:36864
	ds_read_b64_tr_b16 v[130:131], v235 offset:39168
	ds_read_b64_tr_b16 v[126:127], v235 offset:39232
	ds_read_b64_tr_b16 v[124:125], v235 offset:36928
	ds_read_b64_tr_b16 v[132:133], v234 offset:36896
	ds_read_b64_tr_b16 v[134:135], v234 offset:39200
	ds_read_b64_tr_b16 v[122:123], v234 offset:39264
	ds_read_b64_tr_b16 v[120:121], v234 offset:36960
	v_pk_mul_f32 v[106:107], v[180:181], v[106:107]
	v_pk_mul_f32 v[104:105], v[178:179], v[104:105]
	v_pk_mul_f32 v[114:115], v[188:189], v[114:115]
	v_pk_mul_f32 v[112:113], v[186:187], v[112:113]
	s_waitcnt lgkmcnt(14)
	v_mfma_f32_16x16x32_bf16 v[104:107], v[140:143], v[144:147], v[104:107]
	v_mul_f32_e64 v110, v184, v110
	v_mul_f32_e64 v111, v185, v111
	v_pk_mul_f32 v[108:109], v[182:183], v[108:109]
	s_waitcnt lgkmcnt(11)
	v_mfma_f32_16x16x32_bf16 v[144:147], v[140:143], v[236:239], v[112:115]
	s_nop 2
	v_mul_f32_e64 v114, v192, v118
	v_mul_f32_e64 v115, v193, v119
	v_pk_mul_f32 v[112:113], v[190:191], v[116:117]
	v_mfma_f32_16x16x32_bf16 v[108:111], v[140:143], v[152:155], v[108:111]
	s_waitcnt lgkmcnt(9)
	v_mfma_f32_16x16x32_bf16 v[152:155], v[140:143], v[244:247], v[112:115]
	v_mfma_f32_16x16x32_bf16 v[116:119], v[136:139], v[148:151], v[104:107]
	v_mfma_f32_16x16x32_bf16 v[112:115], v[136:139], v[156:159], v[108:111]
	v_mfma_f32_16x16x32_bf16 v[108:111], v[136:139], v[240:243], v[144:147]
	s_waitcnt lgkmcnt(8)
	v_mfma_f32_16x16x32_bf16 v[104:107], v[136:139], v[248:251], v[152:155]
	v_mov_b32_e32 v165, v164
	s_nop 1
	v_pk_mul_f32 v[154:155], v[164:165], v[46:47]
	v_pk_mul_f32 v[152:153], v[174:175], v[44:45]
	v_pk_mul_f32 v[46:47], v[164:165], v[70:71]
	v_pk_mul_f32 v[44:45], v[174:175], v[68:69]
	v_pk_mul_f32 v[158:159], v[164:165], v[58:59]
	v_pk_mul_f32 v[156:157], v[174:175], v[56:57]
	v_pk_mul_f32 v[70:71], v[164:165], v[82:83]
	v_pk_mul_f32 v[68:69], v[174:175], v[80:81]
	v_pk_mul_f32 v[82:83], v[164:165], v[78:79]
	v_pk_mul_f32 v[80:81], v[174:175], v[76:77]
	v_pk_mul_f32 v[58:59], v[164:165], v[94:95]
	v_pk_mul_f32 v[56:57], v[174:175], v[92:93]
	v_pk_mul_f32 v[78:79], v[164:165], v[86:87]
	v_pk_mul_f32 v[76:77], v[174:175], v[84:85]
	v_lshlrev_b32_e32 v84, 16, v140
	v_and_b32_e32 v85, 0xffff0000, v140
	v_lshlrev_b32_e32 v86, 16, v141
	v_and_b32_e32 v87, 0xffff0000, v141
	v_lshlrev_b32_e32 v92, 16, v142
	v_and_b32_e32 v93, 0xffff0000, v142
	v_lshlrev_b32_e32 v94, 16, v143
	v_and_b32_e32 v95, 0xffff0000, v143
	v_mul_f32_e32 v84, v208, v84
	v_mul_f32_e32 v85, v209, v85
	v_mul_f32_e32 v86, v210, v86
	v_mul_f32_e32 v87, v211, v87
	v_mul_f32_e32 v92, v212, v92
	v_mul_f32_e32 v93, v213, v93
	v_mul_f32_e32 v94, v214, v94
	v_mul_f32_e32 v95, v215, v95
	v_pk_mul_f32 v[146:147], v[164:165], v[50:51]
	v_pk_mul_f32 v[144:145], v[174:175], v[48:49]
	v_pk_mul_f32 v[50:51], v[164:165], v[90:91]
	v_pk_mul_f32 v[48:49], v[174:175], v[88:89]
	v_pk_mul_f32 v[90:91], v[164:165], v[74:75]
	v_pk_mul_f32 v[88:89], v[174:175], v[72:73]
	v_pk_mul_f32 v[74:75], v[164:165], v[98:99]
	v_pk_mul_f32 v[72:73], v[174:175], v[96:97]
	v_cvt_pk_bf16_f32 v84, v84, v85
	v_cvt_pk_bf16_f32 v85, v86, v87
	v_cvt_pk_bf16_f32 v86, v92, v93
	v_cvt_pk_bf16_f32 v87, v94, v95
	v_lshlrev_b32_e32 v92, 16, v136
	v_and_b32_e32 v93, 0xffff0000, v136
	v_lshlrev_b32_e32 v94, 16, v137
	v_and_b32_e32 v95, 0xffff0000, v137
	v_lshlrev_b32_e32 v96, 16, v138
	v_and_b32_e32 v97, 0xffff0000, v138
	v_lshlrev_b32_e32 v98, 16, v139
	v_and_b32_e32 v99, 0xffff0000, v139
	v_mul_f32_e32 v92, v216, v92
	v_mul_f32_e32 v93, v217, v93
	v_mul_f32_e32 v94, v218, v94
	v_mul_f32_e32 v95, v219, v95
	v_mul_f32_e32 v96, v220, v96
	v_mul_f32_e32 v97, v221, v97
	v_mul_f32_e32 v98, v222, v98
	v_mul_f32_e32 v99, v223, v99
	v_pk_mul_f32 v[150:151], v[164:165], v[62:63]
	v_pk_mul_f32 v[148:149], v[174:175], v[60:61]
	v_pk_mul_f32 v[62:63], v[164:165], v[102:103]
	v_pk_mul_f32 v[60:61], v[174:175], v[100:101]
	v_cvt_pk_bf16_f32 v100, v92, v93
	v_cvt_pk_bf16_f32 v101, v94, v95
	v_cvt_pk_bf16_f32 v102, v96, v97
	v_cvt_pk_bf16_f32 v103, v98, v99
	ds_read_b64_tr_b16 v[92:93], v235 offset:36992
	ds_read_b64_tr_b16 v[94:95], v235 offset:39296
	ds_read_b64_tr_b16 v[96:97], v234 offset:37024
	ds_read_b64_tr_b16 v[98:99], v234 offset:39328
	ds_read_b64_tr_b16 v[136:137], v235 offset:37056
	ds_read_b64_tr_b16 v[138:139], v235 offset:39360
	ds_read_b64_tr_b16 v[140:141], v234 offset:37088
	ds_read_b64_tr_b16 v[142:143], v234 offset:39392
	v_pk_mul_f32 v[42:43], v[164:165], v[42:43]
	v_pk_mul_f32 v[40:41], v[174:175], v[40:41]
	v_pk_mul_f32 v[54:55], v[164:165], v[54:55]
	v_pk_mul_f32 v[52:53], v[174:175], v[52:53]
	v_pk_mul_f32 v[66:67], v[164:165], v[66:67]
	v_pk_mul_f32 v[64:65], v[174:175], v[64:65]
	s_setprio 1
	s_waitcnt lgkmcnt(14)
	v_mfma_f32_16x16x32_bf16 v[40:43], v[128:131], v[84:87], v[40:43]
	s_waitcnt lgkmcnt(10)
	v_mfma_f32_16x16x32_bf16 v[52:55], v[132:135], v[84:87], v[52:55]
	v_mfma_f32_16x16x32_bf16 v[124:127], v[124:127], v[84:87], v[144:147]
	s_waitcnt lgkmcnt(8)
; __device__ __forceinline__ unsigned cvtpk(float lo, float hi) { unsigned r; asm volatile("v_cvt_pk_bf16_f32 %0, %1, %2" : "=v"(r) : "v"(lo), "v"(hi)); return r; }
; __device__ __forceinline__ bf16x8 cat(s16x4 a, s16x4 b) { return (bf16x8){a[0], a[1], a[2], a[3], b[0], b[1], b[2], b[3]}; }
; #define MF16(a, b, c) __builtin_amdgcn_mfma_f32_16x16x32_bf16((a), (b), (c), 0, 0, 0)
; #define RBAR() do { asm volatile("s_waitcnt lgkmcnt(0)" ::: "memory"); __builtin_amdgcn_s_barrier(); asm volatile("" ::: "memory"); } while (0)
; __device__ __forceinline__ unsigned cvtpk(float lo, float hi) { unsigned r; asm volatile("v_cvt_pk_bf16_f32 %0, %1, %2" : "=v"(r) : "v"(lo), "v"(hi)); return r; }
; #define SCHED() __builtin_amdgcn_sched_barrier(0)
; #define LDS_U(buf, u) do { _Pragma("unroll") for (int k = 0; k < 4; ++k) { LAS unsigned char* pb = ((k & 1) ? pKo : pKe) + 32 * ((u) >> 2) * RSQ + 32 * (4 * ((u) & 3) + k); ua[buf][k][0] = trd(pb); ua[buf][k][1] = trd(pb + 4 * RSQ); } } while (0)
; __device__ __forceinline__ void ret_item(LAS unsigned char* lds, const bf16_t* proj, bf16_t* OD, int b, int h, int dir, int vs, float lg2) {
;     ...
; #pragma unroll
;         for (int u = 0; u < 8; ++u) { if (u < 7) LDS_U((u + 1) & 1, u + 1); SCHED();
;             __builtin_amdgcn_s_setprio(1);
; #pragma unroll
;             for (int k = 0; k < 4; ++k) st[4 * (u & 3) + k] = MF16(cat(ua[u & 1][k][0], ua[u & 1][k][1]), bvd[u >> 2], st[4 * (u & 3) + k]);
;             __builtin_amdgcn_s_setprio(0); SCHED(); }
;     ...
; #pragma unroll
;         for (int it = 0; it < 4; ++it) { u32x2 w; w.x = cvtpk(acc[it][0], acc[it][1]); w.y = cvtpk(acc[it][2], acc[it][3]); *(u32x2*)(Og + (t0 + 16 * it + l15) * 4096) = w; }
;         RBAR();
	v_mfma_f32_16x16x32_bf16 v[120:123], v[120:123], v[84:87], v[152:155]
	s_setprio 0
	ds_read_b64_tr_b16 v[128:129], v235 offset:37120
	ds_read_b64_tr_b16 v[130:131], v235 offset:39424
	ds_read_b64_tr_b16 v[134:135], v235 offset:39488
	ds_read_b64_tr_b16 v[132:133], v235 offset:37184
	ds_read_b64_tr_b16 v[144:145], v234 offset:37152
	ds_read_b64_tr_b16 v[146:147], v234 offset:39456
	ds_read_b64_tr_b16 v[154:155], v234 offset:39520
	ds_read_b64_tr_b16 v[152:153], v234 offset:37216
	s_setprio 1
	s_waitcnt lgkmcnt(14)
	v_mfma_f32_16x16x32_bf16 v[92:95], v[92:95], v[84:87], v[44:47]
	s_waitcnt lgkmcnt(12)
	v_mfma_f32_16x16x32_bf16 v[64:67], v[96:99], v[84:87], v[64:67]
	s_waitcnt lgkmcnt(10)
	v_mfma_f32_16x16x32_bf16 v[96:99], v[136:139], v[84:87], v[148:151]
	s_waitcnt lgkmcnt(8)
	v_mfma_f32_16x16x32_bf16 v[136:139], v[140:143], v[84:87], v[156:159]
	s_setprio 0
	ds_read_b64_tr_b16 v[44:45], v235 offset:37248
	ds_read_b64_tr_b16 v[46:47], v235 offset:39552
	ds_read_b64_tr_b16 v[142:143], v235 offset:39616
	ds_read_b64_tr_b16 v[140:141], v235 offset:37312
	ds_read_b64_tr_b16 v[148:149], v234 offset:37280
	ds_read_b64_tr_b16 v[150:151], v234 offset:39584
	ds_read_b64_tr_b16 v[158:159], v234 offset:39648
	ds_read_b64_tr_b16 v[156:157], v234 offset:37344
	s_setprio 1
	s_waitcnt lgkmcnt(14)
	v_mfma_f32_16x16x32_bf16 v[128:131], v[128:131], v[84:87], v[48:51]
	s_waitcnt lgkmcnt(10)
	v_mfma_f32_16x16x32_bf16 v[144:147], v[144:147], v[84:87], v[68:71]
	v_mfma_f32_16x16x32_bf16 v[132:135], v[132:135], v[84:87], v[80:83]
	s_waitcnt lgkmcnt(8)
	v_mfma_f32_16x16x32_bf16 v[152:155], v[152:155], v[84:87], v[88:91]
	s_setprio 0
	ds_read_b64_tr_b16 v[48:49], v235 offset:55296
	ds_read_b64_tr_b16 v[50:51], v235 offset:57600
	ds_read_b64_tr_b16 v[70:71], v235 offset:57664
	ds_read_b64_tr_b16 v[68:69], v235 offset:55360
	ds_read_b64_tr_b16 v[80:81], v234 offset:55328
	ds_read_b64_tr_b16 v[82:83], v234 offset:57632
	ds_read_b64_tr_b16 v[90:91], v234 offset:57696
	ds_read_b64_tr_b16 v[88:89], v234 offset:55392
	s_setprio 1
	s_waitcnt lgkmcnt(14)
	v_mfma_f32_16x16x32_bf16 v[236:239], v[44:47], v[84:87], v[56:59]
	s_waitcnt lgkmcnt(10)
	v_mfma_f32_16x16x32_bf16 v[148:151], v[148:151], v[84:87], v[76:79]
	v_mfma_f32_16x16x32_bf16 v[140:143], v[140:143], v[84:87], v[72:75]
	s_waitcnt lgkmcnt(8)
	v_mfma_f32_16x16x32_bf16 v[156:159], v[156:159], v[84:87], v[60:63]
	s_setprio 0
	ds_read_b64_tr_b16 v[56:57], v235 offset:55424
	ds_read_b64_tr_b16 v[58:59], v235 offset:57728
	ds_read_b64_tr_b16 v[62:63], v235 offset:57792
	ds_read_b64_tr_b16 v[60:61], v235 offset:55488
	ds_read_b64_tr_b16 v[72:73], v234 offset:55456
	ds_read_b64_tr_b16 v[74:75], v234 offset:57760
	ds_read_b64_tr_b16 v[78:79], v234 offset:57824
	ds_read_b64_tr_b16 v[76:77], v234 offset:55520
	s_setprio 1
	s_waitcnt lgkmcnt(14)
	v_mfma_f32_16x16x32_bf16 v[40:43], v[48:51], v[100:103], v[40:43]
	s_waitcnt lgkmcnt(10)
	v_mfma_f32_16x16x32_bf16 v[52:55], v[80:83], v[100:103], v[52:55]
	v_mfma_f32_16x16x32_bf16 v[48:51], v[68:71], v[100:103], v[124:127]
	s_waitcnt lgkmcnt(8)
	v_mfma_f32_16x16x32_bf16 v[44:47], v[88:91], v[100:103], v[120:123]
	s_setprio 0
	ds_read_b64_tr_b16 v[80:81], v235 offset:55552
	ds_read_b64_tr_b16 v[82:83], v235 offset:57856
	ds_read_b64_tr_b16 v[86:87], v235 offset:57920
	ds_read_b64_tr_b16 v[84:85], v235 offset:55616
	ds_read_b64_tr_b16 v[120:121], v234 offset:55584
	ds_read_b64_tr_b16 v[122:123], v234 offset:57888
	ds_read_b64_tr_b16 v[126:127], v234 offset:57952
	ds_read_b64_tr_b16 v[124:125], v234 offset:55648
	s_setprio 1
	s_waitcnt lgkmcnt(14)
	v_mfma_f32_16x16x32_bf16 v[68:71], v[56:59], v[100:103], v[92:95]
	s_waitcnt lgkmcnt(10)
	v_mfma_f32_16x16x32_bf16 v[64:67], v[72:75], v[100:103], v[64:67]
	v_mfma_f32_16x16x32_bf16 v[60:63], v[60:63], v[100:103], v[96:99]
	s_waitcnt lgkmcnt(8)
	v_mfma_f32_16x16x32_bf16 v[56:59], v[76:79], v[100:103], v[136:139]
	s_setprio 0
	ds_read_b64_tr_b16 v[92:93], v235 offset:55680
	ds_read_b64_tr_b16 v[94:95], v235 offset:57984
	ds_read_b64_tr_b16 v[98:99], v235 offset:58048
	ds_read_b64_tr_b16 v[96:97], v235 offset:55744
	ds_read_b64_tr_b16 v[136:137], v234 offset:55712
	ds_read_b64_tr_b16 v[138:139], v234 offset:58016
	ds_read_b64_tr_b16 v[242:243], v234 offset:58080
	ds_read_b64_tr_b16 v[240:241], v234 offset:55776
	s_setprio 1
	s_waitcnt lgkmcnt(14)
	v_mfma_f32_16x16x32_bf16 v[88:91], v[80:83], v[100:103], v[128:131]
	s_waitcnt lgkmcnt(10)
	v_mfma_f32_16x16x32_bf16 v[80:83], v[120:123], v[100:103], v[144:147]
	v_mfma_f32_16x16x32_bf16 v[76:79], v[84:87], v[100:103], v[132:135]
	s_waitcnt lgkmcnt(8)
	v_mfma_f32_16x16x32_bf16 v[72:75], v[124:127], v[100:103], v[152:155]
	s_setprio 0
	s_setprio 1
	s_waitcnt lgkmcnt(6)
	v_mfma_f32_16x16x32_bf16 v[92:95], v[92:95], v[100:103], v[236:239]
	s_waitcnt lgkmcnt(2)
	v_mfma_f32_16x16x32_bf16 v[84:87], v[136:139], v[100:103], v[148:151]
	v_mfma_f32_16x16x32_bf16 v[96:99], v[96:99], v[100:103], v[140:143]
	s_waitcnt lgkmcnt(0)
	v_mfma_f32_16x16x32_bf16 v[100:103], v[240:243], v[100:103], v[156:159]
	s_setprio 0
	v_lshl_or_b32 v176, v176, 18, v224
	v_cvt_pk_bf16_f32 v116, v116, v117
	v_cvt_pk_bf16_f32 v117, v118, v119
	v_lshl_add_u64 v[118:119], v[176:177], 1, v[160:161]
	global_store_dwordx2 v[118:119], v[116:117], off
	v_cvt_pk_bf16_f32 v112, v112, v113
	v_cvt_pk_bf16_f32 v113, v114, v115
	v_ashrrev_i32_e32 v115, 31, v176
	v_mov_b32_e32 v114, v176
	v_lshl_add_u64 v[114:115], v[114:115], 1, v[160:161]
	s_mov_b32 s20, 0x20000
	v_add_co_u32_e32 v116, vcc, s20, v114
	s_mov_b32 s20, 0x40000
	s_nop 0
	v_addc_co_u32_e32 v117, vcc, 0, v115, vcc
	global_store_dwordx2 v[116:117], v[112:113], off
	v_cvt_pk_bf16_f32 v108, v108, v109
	v_cvt_pk_bf16_f32 v109, v110, v111
	v_add_co_u32_e32 v110, vcc, s20, v114
	s_add_i32 s19, s19, -1
	s_nop 0
	v_addc_co_u32_e32 v111, vcc, 0, v115, vcc
	global_store_dwordx2 v[110:111], v[108:109], off
	v_cvt_pk_bf16_f32 v104, v104, v105
	v_cvt_pk_bf16_f32 v105, v106, v107
	v_add_co_u32_e32 v106, vcc, s65, v114
	s_add_i32 s16, s16, 1
	s_nop 0
	v_addc_co_u32_e32 v107, vcc, 0, v115, vcc
	global_store_dwordx2 v[106:107], v[104:105], off
	s_waitcnt lgkmcnt(0)
	s_barrier
	s_cmp_lg_u32 s19, -2
	s_cbranch_scc0 .LBB0_138
